# P0 w_in conversion: item order remapped so a workgroup's 8 waves write 1KB-contiguous bf16 rows (8 K-blocks x 1 column block)
# baseline (speedup 1.0000x reference)
; __device__ __forceinline__ void p0_transpose_item(const float* W, int K, int N, bf16* WT, int mode, LAS float* scr, int item, int lane, const float* kscale = nullptr) {
;     const int nblk = N / 32, kb = item / nblk, nb = item % nblk, k0 = 64 * kb, n0 = 32 * nb;
;     const int rb = (mode == 0 || mode == 3 || mode == 4) ? n0 : ((n0 >> 7) * 256 + (n0 & 127) + (mode == 2 ? 128 : 0));
;     float wv[32];
; #pragma unroll
;     for (int i = 0; i < 32; ++i) wv[i] = W[(size_t)(k0 + 2 * i + (lane >> 5)) * N + n0 + (lane & 31)];
; template <int WHICH> __device__ __forceinline__ void convert_weights(const Frame& F, int gw, int ngw) {
;     ...
;     for (int it = gw; it < NIT; it += ngw) {
;         if (WHICH == 0) { if (it < I_1) p0_transpose_item(P_w_in, DM, 9248, P_W1, 0, scr, it, F.lane); else p0_transpose_item(P_w_out, DM, DM, P_W2, 4, scr, it - I_1, F.lane); }
.LBB0_12:
	s_lshr_b32 s98, s53, 3
	s_and_b32 s99, s53, 7
	s_mul_hi_i32 s12, s98, 0x71625345
	s_ashr_i32 s12, s12, 7
	s_mul_i32 s13, s12, 0x121
	s_sub_i32 s13, s98, s13
	s_lshl_b32 s12, s12, 3
	s_or_b32 s12, s12, s99
	s_mul_i32 s98, s12, 0x121
	s_add_i32 s98, s98, s13
	s_lshl_b32 s99, s98, 5
	s_mul_hi_i32 s12, s98, 0x71625345
	s_lshr_b32 s13, s12, 31
	s_ashr_i32 s12, s12, 7
	s_load_dwordx2 s[54:55], s[0:1], 0x48
	s_add_i32 s13, s12, s13
	s_lshl_b32 s12, s13, 6
	s_mulk_i32 s13, 0xdbe0
	s_add_i32 s14, s99, s13
	s_ashr_i32 s15, s14, 31
	s_lshl_b64 s[56:57], s[14:15], 2
	s_waitcnt lgkmcnt(0)
	s_add_u32 s54, s54, s56
	v_or_b32_e32 v21, s12, v1
	s_addc_u32 s55, s55, s57
	v_lshl_add_u64 v[22:23], s[54:55], 0, v[2:3]
	v_or_b32_e32 v26, 2, v21
	v_or_b32_e32 v28, 4, v21
	v_or_b32_e32 v30, 6, v21
	v_or_b32_e32 v32, 8, v21
	v_or_b32_e32 v34, 10, v21
	v_or_b32_e32 v36, 12, v21
	v_or_b32_e32 v38, 14, v21
	v_mad_i64_i32 v[24:25], s[54:55], v21, s52, v[22:23]
	v_mad_i64_i32 v[26:27], s[54:55], v26, s52, v[22:23]
	v_mad_i64_i32 v[28:29], s[54:55], v28, s52, v[22:23]
	v_mad_i64_i32 v[30:31], s[54:55], v30, s52, v[22:23]
	v_mad_i64_i32 v[32:33], s[54:55], v32, s52, v[22:23]
	v_mad_i64_i32 v[34:35], s[54:55], v34, s52, v[22:23]
	v_mad_i64_i32 v[36:37], s[54:55], v36, s52, v[22:23]
	v_mad_i64_i32 v[38:39], s[54:55], v38, s52, v[22:23]
	global_load_dword v40, v[24:25], off
	global_load_dword v41, v[26:27], off
	global_load_dword v42, v[28:29], off
	global_load_dword v43, v[30:31], off
	global_load_dword v44, v[32:33], off
	global_load_dword v45, v[34:35], off
	global_load_dword v46, v[36:37], off
	global_load_dword v47, v[38:39], off
	v_or_b32_e32 v24, 16, v21
	v_or_b32_e32 v26, 18, v21
	v_or_b32_e32 v28, 20, v21
	v_or_b32_e32 v30, 22, v21
	v_or_b32_e32 v32, 24, v21
	v_or_b32_e32 v34, 26, v21
	v_or_b32_e32 v36, 28, v21
	v_or_b32_e32 v38, 30, v21
	v_mad_i64_i32 v[24:25], s[54:55], v24, s52, v[22:23]
	v_mad_i64_i32 v[26:27], s[54:55], v26, s52, v[22:23]
	v_mad_i64_i32 v[28:29], s[54:55], v28, s52, v[22:23]
	v_mad_i64_i32 v[30:31], s[54:55], v30, s52, v[22:23]
	v_mad_i64_i32 v[32:33], s[54:55], v32, s52, v[22:23]
	v_mad_i64_i32 v[34:35], s[54:55], v34, s52, v[22:23]
	v_mad_i64_i32 v[36:37], s[54:55], v36, s52, v[22:23]
	v_mad_i64_i32 v[38:39], s[54:55], v38, s52, v[22:23]
	global_load_dword v48, v[24:25], off
	global_load_dword v49, v[26:27], off
	global_load_dword v50, v[28:29], off
	global_load_dword v51, v[30:31], off
	global_load_dword v52, v[32:33], off
	global_load_dword v53, v[34:35], off
	global_load_dword v54, v[36:37], off
	global_load_dword v55, v[38:39], off
	v_or_b32_e32 v24, 32, v21
	v_or_b32_e32 v26, 34, v21
	v_or_b32_e32 v28, 36, v21
	v_or_b32_e32 v30, 38, v21
	v_or_b32_e32 v32, 40, v21
	v_or_b32_e32 v34, 42, v21
	v_or_b32_e32 v36, 44, v21
	v_or_b32_e32 v38, 46, v21
	v_mad_i64_i32 v[24:25], s[54:55], v24, s52, v[22:23]
	v_mad_i64_i32 v[26:27], s[54:55], v26, s52, v[22:23]
	v_mad_i64_i32 v[28:29], s[54:55], v28, s52, v[22:23]
	v_mad_i64_i32 v[30:31], s[54:55], v30, s52, v[22:23]
	v_mad_i64_i32 v[32:33], s[54:55], v32, s52, v[22:23]
	v_mad_i64_i32 v[34:35], s[54:55], v34, s52, v[22:23]
	v_mad_i64_i32 v[36:37], s[54:55], v36, s52, v[22:23]
	v_mad_i64_i32 v[38:39], s[54:55], v38, s52, v[22:23]
	global_load_dword v56, v[24:25], off
	global_load_dword v57, v[26:27], off
	global_load_dword v58, v[28:29], off
	global_load_dword v59, v[30:31], off
	global_load_dword v60, v[32:33], off
	global_load_dword v61, v[34:35], off
	global_load_dword v62, v[36:37], off
	s_nop 0
	global_load_dword v38, v[38:39], off
	v_or_b32_e32 v24, 48, v21
	v_or_b32_e32 v26, 50, v21
	v_or_b32_e32 v28, 52, v21
	v_or_b32_e32 v30, 54, v21
	v_or_b32_e32 v32, 56, v21
	v_or_b32_e32 v34, 58, v21
	v_or_b32_e32 v36, 60, v21
	v_or_b32_e32 v21, 62, v21
	v_mad_i64_i32 v[24:25], s[54:55], v24, s52, v[22:23]
	v_mad_i64_i32 v[26:27], s[54:55], v26, s52, v[22:23]
	v_mad_i64_i32 v[28:29], s[54:55], v28, s52, v[22:23]
	v_mad_i64_i32 v[30:31], s[54:55], v30, s52, v[22:23]
	v_mad_i64_i32 v[32:33], s[54:55], v32, s52, v[22:23]
	v_mad_i64_i32 v[34:35], s[54:55], v34, s52, v[22:23]
	v_mad_i64_i32 v[36:37], s[54:55], v36, s52, v[22:23]
	v_mad_i64_i32 v[22:23], s[54:55], v21, s52, v[22:23]
	global_load_dword v21, v[24:25], off
	s_nop 0
	global_load_dword v24, v[26:27], off
	global_load_dword v25, v[28:29], off
	s_nop 0
	global_load_dword v26, v[30:31], off
	global_load_dword v27, v[32:33], off
	global_load_dword v28, v[34:35], off
	global_load_dword v29, v[36:37], off
	s_nop 0
	global_load_dword v22, v[22:23], off
	s_waitcnt vmcnt(30)
; #define LAS __attribute__((address_space(3)))
; #define LDS_WAIT() asm volatile("s_waitcnt lgkmcnt(0)" ::: "memory")
; __device__ __forceinline__ unsigned cvtpk(float lo, float hi) { f32x2_t v = {lo, hi}; bf16x2_t b = __builtin_convertvector(v, bf16x2_t); return __builtin_bit_cast(unsigned, b); }
; __device__ __forceinline__ void p0_transpose_item(const float* W, int K, int N, bf16* WT, int mode, LAS float* scr, int item, int lane, const float* kscale = nullptr) {
;     ...
; #pragma unroll
;     for (int i = 0; i < 32; ++i) scr[(2 * i + (lane >> 5)) * 33 + (lane & 31)] = wv[i];
;     LDS_WAIT(); asm volatile("" ::: "memory");
;     const int c = lane & 7;
;     f32x4 ks0 = (f32x4){1.f, 1.f, 1.f, 1.f}, ks1 = ks0; if (kscale) { ks0 = *(const f32x4*)(kscale + k0 + 8 * c); ks1 = *(const f32x4*)(kscale + k0 + 8 * c + 4); }
; #pragma unroll
;     for (int j = 0; j < 4; ++j) { const int n = (lane >> 3) + 8 * j; const LAS float* s = scr + (8 * c) * 33 + n;
;         u32x4 o; o.x = cvtpk(s[0 * 33] * ks0.x, s[1 * 33] * ks0.y); o.y = cvtpk(s[2 * 33] * ks0.z, s[3 * 33] * ks0.w); o.z = cvtpk(s[4 * 33] * ks1.x, s[5 * 33] * ks1.y); o.w = cvtpk(s[6 * 33] * ks1.z, s[7 * 33] * ks1.w);
;         const int k0d = (mode == 4) ? ((k0 + 2048) & 4095) : k0;
;         const size_t dst = (mode == 3) ? ((size_t)(((rb + n) >> 8) * (K >> 6) + kb) * 256 + ((rb + n) & 255)) * 64 + 8 * c : (size_t)(rb + n) * K + k0d + 8 * c;
;         *(u32x4*)(WT + dst) = o; }
;     LDS_WAIT(); asm volatile("" ::: "memory");
	ds_write2_b32 v12, v40, v41 offset1:66
	s_waitcnt vmcnt(28)
	ds_write2_b32 v12, v42, v43 offset0:132 offset1:198
	s_waitcnt vmcnt(26)
	ds_write2_b32 v13, v44, v45 offset0:8 offset1:74
	s_waitcnt vmcnt(24)
	ds_write2_b32 v13, v46, v47 offset0:140 offset1:206
	s_waitcnt vmcnt(22)
	ds_write2_b32 v14, v48, v49 offset0:16 offset1:82
	s_waitcnt vmcnt(20)
	ds_write2_b32 v14, v50, v51 offset0:148 offset1:214
	s_waitcnt vmcnt(18)
	ds_write2_b32 v15, v52, v53 offset0:24 offset1:90
	s_waitcnt vmcnt(16)
	ds_write2_b32 v15, v54, v55 offset0:156 offset1:222
	s_waitcnt vmcnt(14)
	ds_write2_b32 v16, v56, v57 offset0:32 offset1:98
	s_waitcnt vmcnt(12)
	ds_write2_b32 v16, v58, v59 offset0:164 offset1:230
	s_waitcnt vmcnt(10)
	ds_write2_b32 v17, v60, v61 offset0:40 offset1:106
	s_waitcnt vmcnt(8)
	ds_write2_b32 v17, v62, v38 offset0:172 offset1:238
	s_waitcnt vmcnt(6)
	ds_write2_b32 v18, v21, v24 offset0:48 offset1:114
	s_waitcnt vmcnt(4)
	ds_write2_b32 v18, v25, v26 offset0:180 offset1:246
	s_waitcnt vmcnt(2)
	ds_write2_b32 v19, v27, v28 offset0:56 offset1:122
	s_waitcnt vmcnt(0)
	ds_write2_b32 v19, v29, v22 offset0:188 offset1:254
	s_waitcnt lgkmcnt(0)
	ds_read2_b32 v[26:27], v8 offset0:33 offset1:41
	ds_read2_b32 v[28:29], v8 offset1:8
	ds_read2_b32 v[30:31], v8 offset0:66 offset1:74
	ds_read2_b32 v[32:33], v8 offset0:99 offset1:107
	ds_read2_b32 v[34:35], v8 offset0:132 offset1:140
	ds_read2_b32 v[36:37], v8 offset0:165 offset1:173
	ds_read2_b32 v[38:39], v8 offset0:198 offset1:206
	ds_read2_b32 v[40:41], v8 offset0:231 offset1:239
	v_add_u32_e32 v42, s14, v7
	s_ashr_i32 s13, s12, 31
	v_ashrrev_i32_e32 v43, 31, v42
	v_lshl_add_u64 v[44:45], s[12:13], 1, v[4:5]
	v_lshlrev_b64 v[46:47], 13, v[42:43]
	s_waitcnt lgkmcnt(6)
	v_cvt_pk_bf16_f32 v22, v28, v26
	s_waitcnt lgkmcnt(4)
	v_cvt_pk_bf16_f32 v23, v30, v32
	s_waitcnt lgkmcnt(2)
	v_cvt_pk_bf16_f32 v24, v34, v36
	s_waitcnt lgkmcnt(0)
	v_cvt_pk_bf16_f32 v25, v38, v40
	v_lshl_add_u64 v[46:47], v[44:45], 0, v[46:47]
	v_add_u32_e32 v26, 8, v42
	global_store_dwordx4 v[46:47], v[22:25], off
	s_nop 1
	v_cvt_pk_bf16_f32 v22, v29, v27
	v_ashrrev_i32_e32 v27, 31, v26
	v_cvt_pk_bf16_f32 v23, v31, v33
	v_cvt_pk_bf16_f32 v24, v35, v37
	v_cvt_pk_bf16_f32 v25, v39, v41
	v_lshlrev_b64 v[26:27], 13, v[26:27]
	ds_read2_b32 v[28:29], v8 offset0:49 offset1:57
	ds_read2_b32 v[30:31], v8 offset0:16 offset1:24
	ds_read2_b32 v[32:33], v8 offset0:82 offset1:90
	ds_read2_b32 v[34:35], v8 offset0:115 offset1:123
	ds_read2_b32 v[36:37], v8 offset0:148 offset1:156
	ds_read2_b32 v[38:39], v8 offset0:181 offset1:189
	ds_read2_b32 v[40:41], v8 offset0:214 offset1:222
	ds_read2_b32 v[46:47], v8 offset0:247 offset1:255
	v_lshl_add_u64 v[26:27], v[44:45], 0, v[26:27]
	global_store_dwordx4 v[26:27], v[22:25], off
	v_add_u32_e32 v26, 16, v42
	v_ashrrev_i32_e32 v27, 31, v26
	v_lshlrev_b64 v[26:27], 13, v[26:27]
	s_waitcnt lgkmcnt(6)
	v_cvt_pk_bf16_f32 v22, v30, v28
	s_waitcnt lgkmcnt(4)
	v_cvt_pk_bf16_f32 v23, v32, v34
	s_waitcnt lgkmcnt(2)
	v_cvt_pk_bf16_f32 v24, v36, v38
	s_waitcnt lgkmcnt(0)
	v_cvt_pk_bf16_f32 v25, v40, v46
	v_lshl_add_u64 v[26:27], v[44:45], 0, v[26:27]
	global_store_dwordx4 v[26:27], v[22:25], off
	v_add_u32_e32 v26, 24, v42
	v_ashrrev_i32_e32 v27, 31, v26
	v_lshlrev_b64 v[26:27], 13, v[26:27]
	v_cvt_pk_bf16_f32 v22, v31, v29
	v_cvt_pk_bf16_f32 v23, v33, v35
	v_cvt_pk_bf16_f32 v24, v37, v39
	v_cvt_pk_bf16_f32 v25, v41, v47
	v_lshl_add_u64 v[26:27], v[44:45], 0, v[26:27]
	global_store_dwordx4 v[26:27], v[22:25], off
	s_waitcnt lgkmcnt(0)
	s_branch .LBB0_8

; #define LAS __attribute__((address_space(3)))
; #define KARG ((const __attribute__((address_space(4))) Args*)__builtin_amdgcn_kernarg_segment_ptr())
; __global__ void __launch_bounds__(NWAVES * 64, 2) hymba_fwd(Args args) {
;     extern __shared__ __attribute__((aligned(16))) unsigned char lds_raw[];
;     Frame F; F.lds = (LAS unsigned char*)lds_raw; F.tid = threadIdx.x; F.lane = F.tid & 63; F.wave = __builtin_amdgcn_readfirstlane(F.tid >> 6); F.G = KARG->grid; F.bid = blockIdx.x;
	.amdhsa_kernel _Z9hymba_fwd4Args
		.amdhsa_group_segment_fixed_size 0
		.amdhsa_private_segment_fixed_size 0
		.amdhsa_kernarg_size 240
		.amdhsa_user_sgpr_count 2
		.amdhsa_user_sgpr_dispatch_ptr 0
		.amdhsa_user_sgpr_queue_ptr 0
		.amdhsa_user_sgpr_kernarg_segment_ptr 1
		.amdhsa_user_sgpr_dispatch_id 0
		.amdhsa_user_sgpr_kernarg_preload_length 0
		.amdhsa_user_sgpr_kernarg_preload_offset 0
		.amdhsa_user_sgpr_private_segment_size 0
		.amdhsa_uses_dynamic_stack 0
		.amdhsa_enable_private_segment 0
		.amdhsa_system_sgpr_workgroup_id_x 1
		.amdhsa_system_sgpr_workgroup_id_y 0
		.amdhsa_system_sgpr_workgroup_id_z 0
		.amdhsa_system_sgpr_workgroup_info 0
		.amdhsa_system_vgpr_workitem_id 0
		.amdhsa_next_free_vgpr 256
		.amdhsa_next_free_sgpr 102
		.amdhsa_accum_offset 256
		.amdhsa_reserve_vcc 1
		.amdhsa_float_round_mode_32 0
		.amdhsa_float_round_mode_16_64 0
		.amdhsa_float_denorm_mode_32 3
		.amdhsa_float_denorm_mode_16_64 3
		.amdhsa_dx10_clamp 1
		.amdhsa_ieee_mode 1
		.amdhsa_fp16_overflow 0
		.amdhsa_tg_split 0
		.amdhsa_exception_fp_ieee_invalid_op 0
		.amdhsa_exception_fp_denorm_src 0
		.amdhsa_exception_fp_ieee_div_zero 0
		.amdhsa_exception_fp_ieee_overflow 0
		.amdhsa_exception_fp_ieee_underflow 0
		.amdhsa_exception_fp_ieee_inexact 0
		.amdhsa_exception_int_div_zero 0
	.end_amdhsa_kernel

; #define LAS __attribute__((address_space(3)))
; #define KARG ((const __attribute__((address_space(4))) Args*)__builtin_amdgcn_kernarg_segment_ptr())
; __global__ void __launch_bounds__(NWAVES * 64, 2) hymba_fwd(Args args) {
;     extern __shared__ __attribute__((aligned(16))) unsigned char lds_raw[];
;     Frame F; F.lds = (LAS unsigned char*)lds_raw; F.tid = threadIdx.x; F.lane = F.tid & 63; F.wave = __builtin_amdgcn_readfirstlane(F.tid >> 6); F.G = KARG->grid; F.bid = blockIdx.x;
amdhsa.kernels:
  - .agpr_count:     0
    .args:
      - .offset:         0
        .size:           240
        .value_kind:     by_value
    .group_segment_fixed_size: 0
    .kernarg_segment_align: 8
    .kernarg_segment_size: 240
    .language:       OpenCL C
    .language_version:
      - 2
      - 0
    .max_flat_workgroup_size: 512
    .name:           _Z9hymba_fwd4Args
    .private_segment_fixed_size: 0
    .sgpr_count:     108
    .sgpr_spill_count: 20
    .symbol:         _Z9hymba_fwd4Args.kd
    .uniform_work_group_size: 1
    .uses_dynamic_stack: false
    .vgpr_count:     256
    .vgpr_spill_count: 0
    .wavefront_size: 64
